# grid barrier: the first workgroup of each XCD to arrive issues an early L2 writeback, so the leader's writeback after the last arrival has less to flush
# baseline (speedup 1.0000x reference)
; __device__ __forceinline__ unsigned xb_ld(unsigned* p)              { return __hip_atomic_load(p, __ATOMIC_RELAXED, __HIP_MEMORY_SCOPE_AGENT); }
; __device__ __forceinline__ unsigned xb_add(unsigned* p, unsigned v) { return __hip_atomic_fetch_add(p, v, __ATOMIC_RELAXED, __HIP_MEMORY_SCOPE_AGENT); }
; #define XB_SPIN(cond, bar) do { unsigned _sp = 0; while (cond) { __builtin_amdgcn_s_sleep(1); \
;     if ((++_sp & 255u) == 0u) { if (xb_ld(&(bar)[XB_TMO])) break; if (_sp > XB_SPIN_CAP) { atomicAdd(&(bar)[XB_TMO], 1u); break; } } } } while (0)
; __device__ __forceinline__ void xcd_barrier(const XcdBarrier& b) {
;     ...
;         const unsigned old = xb_add(&bar[XB_XSUB(b.x)], 1u);
;         const unsigned gen = old / nloc;
;         if (old + 1u == (gen + 1u) * nloc) {
;             __builtin_amdgcn_fence(__ATOMIC_RELEASE, "agent");
;             asm volatile("s_waitcnt vmcnt(0)" ::: "memory");
;             const unsigned og = xb_add(&bar[XB_TOP], 1u);
;             const unsigned tg = og / nx;
;             if (og + 1u == (tg + 1u) * nx) xb_add(&bar[XB_TOPGEN], 1u);
;             else XB_SPIN(xb_ld(&bar[XB_TOPGEN]) == tg, bar);
;             __builtin_amdgcn_fence(__ATOMIC_ACQUIRE, "agent");
;             xb_add(&bar[XB_XGEN(b.x)], 1u);
;             asm volatile("s_waitcnt vmcnt(0)" ::: "memory");
;         } else {
;             XB_SPIN(xb_ld(&bar[XB_XGEN(b.x)]) == gen, bar);
.LBB0_811:
	v_readlane_b32 s0, v254, 6
	s_lshl_b32 s26, s0, 6
	s_lshl_b64 s[2:3], s[26:27], 2
	v_readlane_b32 s8, v254, 11
	v_readlane_b32 s9, v254, 12
	s_add_u32 s8, s8, s2
	s_addc_u32 s9, s9, s3
	v_mov_b32_e32 v1, 0x1000
	v_sub_u32_e32 v4, 0, v2
	s_nop 0
	global_atomic_add v3, v1, v222, s[8:9] offset:1024 sc0
	v_cvt_f32_u32_e32 v1, v2
	v_rcp_iflag_f32_e32 v1, v1
	s_nop 0
	v_mul_f32_e32 v1, 0x4f7ffffe, v1
	v_cvt_u32_f32_e32 v1, v1
	v_mul_lo_u32 v4, v4, v1
	v_mul_hi_u32 v4, v1, v4
	v_add_u32_e32 v1, v1, v4
	s_waitcnt vmcnt(0)
	v_mul_hi_u32 v1, v3, v1
	v_mul_lo_u32 v4, v1, v2
	v_sub_u32_e32 v4, v3, v4
	v_add_u32_e32 v5, 1, v1
	v_cmp_ge_u32_e32 vcc, v4, v2
	v_add_u32_e32 v3, 1, v3
	s_nop 0
	v_cndmask_b32_e32 v1, v1, v5, vcc
	v_sub_u32_e32 v5, v4, v2
	v_cndmask_b32_e32 v4, v4, v5, vcc
	v_add_u32_e32 v5, 1, v1
	v_cmp_ge_u32_e32 vcc, v4, v2
	s_nop 1
	v_cndmask_b32_e32 v1, v1, v5, vcc
	v_mul_lo_u32 v4, v2, v1
	v_add_u32_e32 v2, v4, v2
	v_cmp_ne_u32_e32 vcc, v3, v2
	s_and_saveexec_b64 s[2:3], vcc
	s_xor_b64 s[10:11], exec, s[2:3]
	s_cbranch_execz .LBB0_824
	s_waitcnt lgkmcnt(0)
	v_add_u32_e32 v5, 1, v4
	v_cmp_eq_u32_e32 vcc, v3, v5
	s_cbranch_vccz .Lxb_nofirst
	buffer_wbl2 sc1
.Lxb_nofirst:
	v_readlane_b32 s14, v254, 11
	v_readlane_b32 s15, v254, 12
	s_nop 1
	s_add_u32 s14, s14, 0x3500
	s_addc_u32 s15, s15, 0
	global_load_dword v0, v169, s[14:15] sc1
	s_waitcnt vmcnt(0)
	v_cmp_eq_u32_e32 vcc, v0, v1
	s_and_saveexec_b64 s[12:13], vcc
	s_cbranch_execz .LBB0_823
	s_mov_b32 s0, 1
	s_mov_b64 s[20:21], 0
	s_branch .LBB0_815
